# v35 + sparse QK epilogue pipelining + DPP scan in select + indexer m0 reordering (combined micro-tweaks)
# speedup vs baseline: 1.0065x; 1.0065x over previous
.Lqk_fast:
	v_lshlrev_b32_e32 v24, 4, v55
	v_lshl_add_u32 v25, v56, 2, s66
	ds_read_b32 v16, v25 offset:6400
	ds_read_b32 v17, v25 offset:6464
	ds_read_b32 v18, v25 offset:6528
	ds_read_b32 v19, v25 offset:6592
	s_waitcnt lgkmcnt(3)
	v_add_u32_e32 v26, s42, v16
	v_lshl_add_u32 v26, v26, 9, v24
	global_load_dwordx4 v[130:133], v26, s[44:45]
	global_load_dwordx4 v[134:137], v26, s[44:45] offset:64
	global_load_dwordx4 v[138:141], v26, s[44:45] offset:128
	global_load_dwordx4 v[142:145], v26, s[44:45] offset:192
	s_waitcnt lgkmcnt(2)
	v_add_u32_e32 v27, s42, v17
	v_lshl_add_u32 v27, v27, 9, v24
	global_load_dwordx4 v[146:149], v27, s[44:45]
	global_load_dwordx4 v[150:153], v27, s[44:45] offset:64
	global_load_dwordx4 v[154:157], v27, s[44:45] offset:128
	global_load_dwordx4 v[158:161], v27, s[44:45] offset:192
	s_waitcnt lgkmcnt(1)
	v_add_u32_e32 v28, s42, v18
	v_lshl_add_u32 v28, v28, 9, v24
	global_load_dwordx4 v[162:165], v28, s[44:45]
	global_load_dwordx4 v[166:169], v28, s[44:45] offset:64
	global_load_dwordx4 v[170:173], v28, s[44:45] offset:128
	global_load_dwordx4 v[174:177], v28, s[44:45] offset:192
	s_waitcnt lgkmcnt(0)
	v_add_u32_e32 v29, s42, v19
	v_lshl_add_u32 v29, v29, 9, v24
	global_load_dwordx4 v[178:181], v29, s[44:45]
	global_load_dwordx4 v[182:185], v29, s[44:45] offset:64
	global_load_dwordx4 v[186:189], v29, s[44:45] offset:128
	global_load_dwordx4 v[190:193], v29, s[44:45] offset:192
	ds_read_b32 v20, v25 offset:6656
	ds_read_b32 v21, v25 offset:6720
	ds_read_b32 v22, v25 offset:6784
	ds_read_b32 v23, v25 offset:6848
	s_waitcnt lgkmcnt(3)
	v_add_u32_e32 v26, s42, v20
	v_lshl_add_u32 v26, v26, 9, v24
	global_load_dwordx4 v[210:213], v26, s[44:45]
	global_load_dwordx4 v[214:217], v26, s[44:45] offset:64
	global_load_dwordx4 v[218:221], v26, s[44:45] offset:128
	global_load_dwordx4 v[222:225], v26, s[44:45] offset:192
	s_waitcnt lgkmcnt(2)
	v_add_u32_e32 v27, s42, v21
	v_lshl_add_u32 v27, v27, 9, v24
	global_load_dwordx4 v[226:229], v27, s[44:45]
	global_load_dwordx4 v[230:233], v27, s[44:45] offset:64
	global_load_dwordx4 v[234:237], v27, s[44:45] offset:128
	global_load_dwordx4 v[238:241], v27, s[44:45] offset:192
	s_waitcnt lgkmcnt(1)
	v_add_u32_e32 v28, s42, v22
	v_lshl_add_u32 v28, v28, 9, v24
	global_load_dwordx4 v[70:73], v28, s[44:45]
	global_load_dwordx4 v[74:77], v28, s[44:45] offset:64
	global_load_dwordx4 v[78:81], v28, s[44:45] offset:128
	global_load_dwordx4 v[82:85], v28, s[44:45] offset:192
	s_waitcnt lgkmcnt(0)
	v_add_u32_e32 v29, s42, v23
	v_lshl_add_u32 v29, v29, 9, v24
	global_load_dwordx4 v[196:199], v29, s[44:45]
	global_load_dwordx4 v[200:203], v29, s[44:45] offset:64
	global_load_dwordx4 v[244:247], v29, s[44:45] offset:128
	global_load_dwordx4 v[248:251], v29, s[44:45] offset:192
	v_subrev_u32_e32 v30, s80, v16
	v_max_i32_e32 v30, 0xffffff80, v30
	v_lshl_add_u32 v30, v30, 2, s72
	ds_read2st64_b32 v[40:41], v30 offset0:2 offset1:5
	ds_read2st64_b32 v[42:43], v30 offset0:8 offset1:11
	s_waitcnt vmcnt(31)
	v_mfma_f32_16x16x32_bf16 v[32:35], v[4:7], v[130:133], 0
	s_waitcnt vmcnt(30)
	v_mfma_f32_16x16x32_bf16 v[32:35], v[0:3], v[134:137], v[32:35]
	s_waitcnt vmcnt(29)
	v_mfma_f32_16x16x32_bf16 v[32:35], v[12:15], v[138:141], v[32:35]
	s_waitcnt vmcnt(28)
	v_mfma_f32_16x16x32_bf16 v[32:35], v[8:11], v[142:145], v[32:35]
	v_subrev_u32_e32 v30, s80, v17
	v_max_i32_e32 v30, 0xffffff80, v30
	v_lshl_add_u32 v30, v30, 2, s72
	ds_read2st64_b32 v[44:45], v30 offset0:2 offset1:5
	ds_read2st64_b32 v[46:47], v30 offset0:8 offset1:11
	s_waitcnt vmcnt(27)
	v_mfma_f32_16x16x32_bf16 v[36:39], v[4:7], v[146:149], 0
	s_waitcnt vmcnt(26)
	v_mfma_f32_16x16x32_bf16 v[36:39], v[0:3], v[150:153], v[36:39]
	s_waitcnt vmcnt(25)
	v_mfma_f32_16x16x32_bf16 v[36:39], v[12:15], v[154:157], v[36:39]
	s_waitcnt vmcnt(24)
	v_mfma_f32_16x16x32_bf16 v[36:39], v[8:11], v[158:161], v[36:39]
	v_add_u32_e32 v31, 0, v87
	s_waitcnt lgkmcnt(2)
	v_fmamk_f32 v32, v32, 0x3db504f3, v40
	v_fmac_f32_e32 v41, 0x3db504f3, v33
	v_fmamk_f32 v34, v34, 0x3db504f3, v42
	v_fmac_f32_e32 v43, 0x3db504f3, v35
	v_mov_b32_e32 v33, v41
	v_mov_b32_e32 v35, v43
	s_mov_b64 exec, s[6:7]
	ds_write_b128 v31, v[32:35]
	s_mov_b64 exec, -1
	v_subrev_u32_e32 v30, s80, v18
	v_max_i32_e32 v30, 0xffffff80, v30
	v_lshl_add_u32 v30, v30, 2, s72
	ds_read2st64_b32 v[40:41], v30 offset0:2 offset1:5
	ds_read2st64_b32 v[42:43], v30 offset0:8 offset1:11
	s_waitcnt vmcnt(23)
	v_mfma_f32_16x16x32_bf16 v[32:35], v[4:7], v[162:165], 0
	s_waitcnt vmcnt(22)
	v_mfma_f32_16x16x32_bf16 v[32:35], v[0:3], v[166:169], v[32:35]
	s_waitcnt vmcnt(21)
	v_mfma_f32_16x16x32_bf16 v[32:35], v[12:15], v[170:173], v[32:35]
	s_waitcnt vmcnt(20)
	v_mfma_f32_16x16x32_bf16 v[32:35], v[8:11], v[174:177], v[32:35]
	v_add_u32_e32 v31, 256, v87
	s_waitcnt lgkmcnt(3)
	v_fmamk_f32 v36, v36, 0x3db504f3, v44
	v_fmac_f32_e32 v45, 0x3db504f3, v37
	v_fmamk_f32 v38, v38, 0x3db504f3, v46
	v_fmac_f32_e32 v47, 0x3db504f3, v39
	v_mov_b32_e32 v37, v45
	v_mov_b32_e32 v39, v47
	s_mov_b64 exec, s[6:7]
	ds_write_b128 v31, v[36:39]
	s_mov_b64 exec, -1
	v_subrev_u32_e32 v30, s80, v19
	v_max_i32_e32 v30, 0xffffff80, v30
	v_lshl_add_u32 v30, v30, 2, s72
	ds_read2st64_b32 v[44:45], v30 offset0:2 offset1:5
	ds_read2st64_b32 v[46:47], v30 offset0:8 offset1:11
	s_waitcnt vmcnt(19)
	v_mfma_f32_16x16x32_bf16 v[36:39], v[4:7], v[178:181], 0
	s_waitcnt vmcnt(18)
	v_mfma_f32_16x16x32_bf16 v[36:39], v[0:3], v[182:185], v[36:39]
	s_waitcnt vmcnt(17)
	v_mfma_f32_16x16x32_bf16 v[36:39], v[12:15], v[186:189], v[36:39]
	s_waitcnt vmcnt(16)
	v_mfma_f32_16x16x32_bf16 v[36:39], v[8:11], v[190:193], v[36:39]
	v_add_u32_e32 v31, 512, v87
	s_waitcnt lgkmcnt(3)
	v_fmamk_f32 v32, v32, 0x3db504f3, v40
	v_fmac_f32_e32 v41, 0x3db504f3, v33
	v_fmamk_f32 v34, v34, 0x3db504f3, v42
	v_fmac_f32_e32 v43, 0x3db504f3, v35
	v_mov_b32_e32 v33, v41
	v_mov_b32_e32 v35, v43
	s_mov_b64 exec, s[6:7]
	ds_write_b128 v31, v[32:35]
	s_mov_b64 exec, -1
	s_nop 7
	s_nop 1
	v_add_u32_e32 v31, 768, v87
	s_waitcnt lgkmcnt(0)
	v_fmamk_f32 v36, v36, 0x3db504f3, v44
	v_fmac_f32_e32 v45, 0x3db504f3, v37
	v_fmamk_f32 v38, v38, 0x3db504f3, v46
	v_fmac_f32_e32 v47, 0x3db504f3, v39
	v_mov_b32_e32 v37, v45
	v_mov_b32_e32 v39, v47
	s_mov_b64 exec, s[6:7]
	ds_write_b128 v31, v[36:39]
	s_mov_b64 exec, -1
	ds_read_b32 v16, v25 offset:6912
	ds_read_b32 v17, v25 offset:6976
	ds_read_b32 v18, v25 offset:7040
	ds_read_b32 v19, v25 offset:7104
	s_waitcnt lgkmcnt(3)
	v_add_u32_e32 v26, s42, v16
	v_lshl_add_u32 v26, v26, 9, v24
	global_load_dwordx4 v[130:133], v26, s[44:45]
	global_load_dwordx4 v[134:137], v26, s[44:45] offset:64
	global_load_dwordx4 v[138:141], v26, s[44:45] offset:128
	global_load_dwordx4 v[142:145], v26, s[44:45] offset:192
	s_waitcnt lgkmcnt(2)
	v_add_u32_e32 v27, s42, v17
	v_lshl_add_u32 v27, v27, 9, v24
	global_load_dwordx4 v[146:149], v27, s[44:45]
	global_load_dwordx4 v[150:153], v27, s[44:45] offset:64
	global_load_dwordx4 v[154:157], v27, s[44:45] offset:128
	global_load_dwordx4 v[158:161], v27, s[44:45] offset:192
	s_waitcnt lgkmcnt(1)
	v_add_u32_e32 v28, s42, v18
	v_lshl_add_u32 v28, v28, 9, v24
	global_load_dwordx4 v[162:165], v28, s[44:45]
	global_load_dwordx4 v[166:169], v28, s[44:45] offset:64
	global_load_dwordx4 v[170:173], v28, s[44:45] offset:128
	global_load_dwordx4 v[174:177], v28, s[44:45] offset:192
	s_waitcnt lgkmcnt(0)
	v_add_u32_e32 v29, s42, v19
	v_lshl_add_u32 v29, v29, 9, v24
	global_load_dwordx4 v[178:181], v29, s[44:45]
	global_load_dwordx4 v[182:185], v29, s[44:45] offset:64
	global_load_dwordx4 v[186:189], v29, s[44:45] offset:128
	global_load_dwordx4 v[190:193], v29, s[44:45] offset:192
	v_subrev_u32_e32 v30, s80, v20
	v_max_i32_e32 v30, 0xffffff80, v30
	v_lshl_add_u32 v30, v30, 2, s72
	ds_read2st64_b32 v[40:41], v30 offset0:2 offset1:5
	ds_read2st64_b32 v[42:43], v30 offset0:8 offset1:11
	s_waitcnt vmcnt(31)
	v_mfma_f32_16x16x32_bf16 v[32:35], v[4:7], v[210:213], 0
	s_waitcnt vmcnt(30)
	v_mfma_f32_16x16x32_bf16 v[32:35], v[0:3], v[214:217], v[32:35]
	s_waitcnt vmcnt(29)
	v_mfma_f32_16x16x32_bf16 v[32:35], v[12:15], v[218:221], v[32:35]
	s_waitcnt vmcnt(28)
	v_mfma_f32_16x16x32_bf16 v[32:35], v[8:11], v[222:225], v[32:35]
	v_subrev_u32_e32 v30, s80, v21
	v_max_i32_e32 v30, 0xffffff80, v30
	v_lshl_add_u32 v30, v30, 2, s72
	ds_read2st64_b32 v[44:45], v30 offset0:2 offset1:5
	ds_read2st64_b32 v[46:47], v30 offset0:8 offset1:11
	s_waitcnt vmcnt(27)
	v_mfma_f32_16x16x32_bf16 v[36:39], v[4:7], v[226:229], 0
	s_waitcnt vmcnt(26)
	v_mfma_f32_16x16x32_bf16 v[36:39], v[0:3], v[230:233], v[36:39]
	s_waitcnt vmcnt(25)
	v_mfma_f32_16x16x32_bf16 v[36:39], v[12:15], v[234:237], v[36:39]
	s_waitcnt vmcnt(24)
	v_mfma_f32_16x16x32_bf16 v[36:39], v[8:11], v[238:241], v[36:39]
	v_add_u32_e32 v31, 1024, v87
	s_waitcnt lgkmcnt(2)
	v_fmamk_f32 v32, v32, 0x3db504f3, v40
	v_fmac_f32_e32 v41, 0x3db504f3, v33
	v_fmamk_f32 v34, v34, 0x3db504f3, v42
	v_fmac_f32_e32 v43, 0x3db504f3, v35
	v_mov_b32_e32 v33, v41
	v_mov_b32_e32 v35, v43
	s_mov_b64 exec, s[6:7]
	ds_write_b128 v31, v[32:35]
	s_mov_b64 exec, -1
	v_subrev_u32_e32 v30, s80, v22
	v_max_i32_e32 v30, 0xffffff80, v30
	v_lshl_add_u32 v30, v30, 2, s72
	ds_read2st64_b32 v[40:41], v30 offset0:2 offset1:5
	ds_read2st64_b32 v[42:43], v30 offset0:8 offset1:11
	s_waitcnt vmcnt(23)
	v_mfma_f32_16x16x32_bf16 v[32:35], v[4:7], v[70:73], 0
	s_waitcnt vmcnt(22)
	v_mfma_f32_16x16x32_bf16 v[32:35], v[0:3], v[74:77], v[32:35]
	s_waitcnt vmcnt(21)
	v_mfma_f32_16x16x32_bf16 v[32:35], v[12:15], v[78:81], v[32:35]
	s_waitcnt vmcnt(20)
	v_mfma_f32_16x16x32_bf16 v[32:35], v[8:11], v[82:85], v[32:35]
	v_add_u32_e32 v31, 1280, v87
	s_waitcnt lgkmcnt(3)
	v_fmamk_f32 v36, v36, 0x3db504f3, v44
	v_fmac_f32_e32 v45, 0x3db504f3, v37
	v_fmamk_f32 v38, v38, 0x3db504f3, v46
	v_fmac_f32_e32 v47, 0x3db504f3, v39
	v_mov_b32_e32 v37, v45
	v_mov_b32_e32 v39, v47
	s_mov_b64 exec, s[6:7]
	ds_write_b128 v31, v[36:39]
	s_mov_b64 exec, -1
	v_subrev_u32_e32 v30, s80, v23
	v_max_i32_e32 v30, 0xffffff80, v30
	v_lshl_add_u32 v30, v30, 2, s72
	ds_read2st64_b32 v[44:45], v30 offset0:2 offset1:5
	ds_read2st64_b32 v[46:47], v30 offset0:8 offset1:11
	s_waitcnt vmcnt(19)
	v_mfma_f32_16x16x32_bf16 v[36:39], v[4:7], v[196:199], 0
	s_waitcnt vmcnt(18)
	v_mfma_f32_16x16x32_bf16 v[36:39], v[0:3], v[200:203], v[36:39]
	s_waitcnt vmcnt(17)
	v_mfma_f32_16x16x32_bf16 v[36:39], v[12:15], v[244:247], v[36:39]
	s_waitcnt vmcnt(16)
	v_mfma_f32_16x16x32_bf16 v[36:39], v[8:11], v[248:251], v[36:39]
	v_add_u32_e32 v31, 1536, v87
	s_waitcnt lgkmcnt(3)
	v_fmamk_f32 v32, v32, 0x3db504f3, v40
	v_fmac_f32_e32 v41, 0x3db504f3, v33
	v_fmamk_f32 v34, v34, 0x3db504f3, v42
	v_fmac_f32_e32 v43, 0x3db504f3, v35
	v_mov_b32_e32 v33, v41
	v_mov_b32_e32 v35, v43
	s_mov_b64 exec, s[6:7]
	ds_write_b128 v31, v[32:35]
	s_mov_b64 exec, -1
	s_nop 7
	s_nop 1
	v_add_u32_e32 v31, 1792, v87
	s_waitcnt lgkmcnt(0)
	v_fmamk_f32 v36, v36, 0x3db504f3, v44
	v_fmac_f32_e32 v45, 0x3db504f3, v37
	v_fmamk_f32 v38, v38, 0x3db504f3, v46
	v_fmac_f32_e32 v47, 0x3db504f3, v39
	v_mov_b32_e32 v37, v45
	v_mov_b32_e32 v39, v47
	s_mov_b64 exec, s[6:7]
	ds_write_b128 v31, v[36:39]
	s_mov_b64 exec, -1
	ds_read_b32 v20, v25 offset:7168
	ds_read_b32 v21, v25 offset:7232
	ds_read_b32 v22, v25 offset:7296
	ds_read_b32 v23, v25 offset:7360
	s_waitcnt lgkmcnt(3)
	v_add_u32_e32 v26, s42, v20
	v_lshl_add_u32 v26, v26, 9, v24
	global_load_dwordx4 v[210:213], v26, s[44:45]
	global_load_dwordx4 v[214:217], v26, s[44:45] offset:64
	global_load_dwordx4 v[218:221], v26, s[44:45] offset:128
	global_load_dwordx4 v[222:225], v26, s[44:45] offset:192
	s_waitcnt lgkmcnt(2)
	v_add_u32_e32 v27, s42, v21
	v_lshl_add_u32 v27, v27, 9, v24
	global_load_dwordx4 v[226:229], v27, s[44:45]
	global_load_dwordx4 v[230:233], v27, s[44:45] offset:64
	global_load_dwordx4 v[234:237], v27, s[44:45] offset:128
	global_load_dwordx4 v[238:241], v27, s[44:45] offset:192
	s_waitcnt lgkmcnt(1)
	v_add_u32_e32 v28, s42, v22
	v_lshl_add_u32 v28, v28, 9, v24
	global_load_dwordx4 v[70:73], v28, s[44:45]
	global_load_dwordx4 v[74:77], v28, s[44:45] offset:64
	global_load_dwordx4 v[78:81], v28, s[44:45] offset:128
	global_load_dwordx4 v[82:85], v28, s[44:45] offset:192
	s_waitcnt lgkmcnt(0)
	v_add_u32_e32 v29, s42, v23
	v_lshl_add_u32 v29, v29, 9, v24
	global_load_dwordx4 v[196:199], v29, s[44:45]
	global_load_dwordx4 v[200:203], v29, s[44:45] offset:64
	global_load_dwordx4 v[244:247], v29, s[44:45] offset:128
	global_load_dwordx4 v[248:251], v29, s[44:45] offset:192
	v_subrev_u32_e32 v30, s80, v16
	v_max_i32_e32 v30, 0xffffff80, v30
	v_lshl_add_u32 v30, v30, 2, s72
	ds_read2st64_b32 v[40:41], v30 offset0:2 offset1:5
	ds_read2st64_b32 v[42:43], v30 offset0:8 offset1:11
	s_waitcnt vmcnt(31)
	v_mfma_f32_16x16x32_bf16 v[32:35], v[4:7], v[130:133], 0
	s_waitcnt vmcnt(30)
	v_mfma_f32_16x16x32_bf16 v[32:35], v[0:3], v[134:137], v[32:35]
	s_waitcnt vmcnt(29)
	v_mfma_f32_16x16x32_bf16 v[32:35], v[12:15], v[138:141], v[32:35]
	s_waitcnt vmcnt(28)
	v_mfma_f32_16x16x32_bf16 v[32:35], v[8:11], v[142:145], v[32:35]
	v_subrev_u32_e32 v30, s80, v17
	v_max_i32_e32 v30, 0xffffff80, v30
	v_lshl_add_u32 v30, v30, 2, s72
	ds_read2st64_b32 v[44:45], v30 offset0:2 offset1:5
	ds_read2st64_b32 v[46:47], v30 offset0:8 offset1:11
	s_waitcnt vmcnt(27)
	v_mfma_f32_16x16x32_bf16 v[36:39], v[4:7], v[146:149], 0
	s_waitcnt vmcnt(26)
	v_mfma_f32_16x16x32_bf16 v[36:39], v[0:3], v[150:153], v[36:39]
	s_waitcnt vmcnt(25)
	v_mfma_f32_16x16x32_bf16 v[36:39], v[12:15], v[154:157], v[36:39]
	s_waitcnt vmcnt(24)
	v_mfma_f32_16x16x32_bf16 v[36:39], v[8:11], v[158:161], v[36:39]
	v_add_u32_e32 v31, 2048, v87
	s_waitcnt lgkmcnt(2)
	v_fmamk_f32 v32, v32, 0x3db504f3, v40
	v_fmac_f32_e32 v41, 0x3db504f3, v33
	v_fmamk_f32 v34, v34, 0x3db504f3, v42
	v_fmac_f32_e32 v43, 0x3db504f3, v35
	v_mov_b32_e32 v33, v41
	v_mov_b32_e32 v35, v43
	s_mov_b64 exec, s[6:7]
	ds_write_b128 v31, v[32:35]
	s_mov_b64 exec, -1
	v_subrev_u32_e32 v30, s80, v18
	v_max_i32_e32 v30, 0xffffff80, v30
	v_lshl_add_u32 v30, v30, 2, s72
	ds_read2st64_b32 v[40:41], v30 offset0:2 offset1:5
	ds_read2st64_b32 v[42:43], v30 offset0:8 offset1:11
	s_waitcnt vmcnt(23)
	v_mfma_f32_16x16x32_bf16 v[32:35], v[4:7], v[162:165], 0
	s_waitcnt vmcnt(22)
	v_mfma_f32_16x16x32_bf16 v[32:35], v[0:3], v[166:169], v[32:35]
	s_waitcnt vmcnt(21)
	v_mfma_f32_16x16x32_bf16 v[32:35], v[12:15], v[170:173], v[32:35]
	s_waitcnt vmcnt(20)
	v_mfma_f32_16x16x32_bf16 v[32:35], v[8:11], v[174:177], v[32:35]
	v_add_u32_e32 v31, 2304, v87
	s_waitcnt lgkmcnt(3)
	v_fmamk_f32 v36, v36, 0x3db504f3, v44
	v_fmac_f32_e32 v45, 0x3db504f3, v37
	v_fmamk_f32 v38, v38, 0x3db504f3, v46
	v_fmac_f32_e32 v47, 0x3db504f3, v39
	v_mov_b32_e32 v37, v45
	v_mov_b32_e32 v39, v47
	s_mov_b64 exec, s[6:7]
	ds_write_b128 v31, v[36:39]
	s_mov_b64 exec, -1
	v_subrev_u32_e32 v30, s80, v19
	v_max_i32_e32 v30, 0xffffff80, v30
	v_lshl_add_u32 v30, v30, 2, s72
	ds_read2st64_b32 v[44:45], v30 offset0:2 offset1:5
	ds_read2st64_b32 v[46:47], v30 offset0:8 offset1:11
	s_waitcnt vmcnt(19)
	v_mfma_f32_16x16x32_bf16 v[36:39], v[4:7], v[178:181], 0
	s_waitcnt vmcnt(18)
	v_mfma_f32_16x16x32_bf16 v[36:39], v[0:3], v[182:185], v[36:39]
	s_waitcnt vmcnt(17)
	v_mfma_f32_16x16x32_bf16 v[36:39], v[12:15], v[186:189], v[36:39]
	s_waitcnt vmcnt(16)
	v_mfma_f32_16x16x32_bf16 v[36:39], v[8:11], v[190:193], v[36:39]
	v_add_u32_e32 v31, 2560, v87
	s_waitcnt lgkmcnt(3)
	v_fmamk_f32 v32, v32, 0x3db504f3, v40
	v_fmac_f32_e32 v41, 0x3db504f3, v33
	v_fmamk_f32 v34, v34, 0x3db504f3, v42
	v_fmac_f32_e32 v43, 0x3db504f3, v35
	v_mov_b32_e32 v33, v41
	v_mov_b32_e32 v35, v43
	s_mov_b64 exec, s[6:7]
	ds_write_b128 v31, v[32:35]
	s_mov_b64 exec, -1
	s_nop 7
	s_nop 1
	v_add_u32_e32 v31, 2816, v87
	s_waitcnt lgkmcnt(0)
	v_fmamk_f32 v36, v36, 0x3db504f3, v44
	v_fmac_f32_e32 v45, 0x3db504f3, v37
	v_fmamk_f32 v38, v38, 0x3db504f3, v46
	v_fmac_f32_e32 v47, 0x3db504f3, v39
	v_mov_b32_e32 v37, v45
	v_mov_b32_e32 v39, v47
	s_mov_b64 exec, s[6:7]
	ds_write_b128 v31, v[36:39]
	s_mov_b64 exec, -1
	v_subrev_u32_e32 v30, s80, v20
	v_max_i32_e32 v30, 0xffffff80, v30
	v_lshl_add_u32 v30, v30, 2, s72
	ds_read2st64_b32 v[40:41], v30 offset0:2 offset1:5
	ds_read2st64_b32 v[42:43], v30 offset0:8 offset1:11
	s_waitcnt vmcnt(15)
	v_mfma_f32_16x16x32_bf16 v[32:35], v[4:7], v[210:213], 0
	s_waitcnt vmcnt(14)
	v_mfma_f32_16x16x32_bf16 v[32:35], v[0:3], v[214:217], v[32:35]
	s_waitcnt vmcnt(13)
	v_mfma_f32_16x16x32_bf16 v[32:35], v[12:15], v[218:221], v[32:35]
	s_waitcnt vmcnt(12)
	v_mfma_f32_16x16x32_bf16 v[32:35], v[8:11], v[222:225], v[32:35]
	v_subrev_u32_e32 v30, s80, v21
	v_max_i32_e32 v30, 0xffffff80, v30
	v_lshl_add_u32 v30, v30, 2, s72
	ds_read2st64_b32 v[44:45], v30 offset0:2 offset1:5
	ds_read2st64_b32 v[46:47], v30 offset0:8 offset1:11
	s_waitcnt vmcnt(11)
	v_mfma_f32_16x16x32_bf16 v[36:39], v[4:7], v[226:229], 0
	s_waitcnt vmcnt(10)
	v_mfma_f32_16x16x32_bf16 v[36:39], v[0:3], v[230:233], v[36:39]
	s_waitcnt vmcnt(9)
	v_mfma_f32_16x16x32_bf16 v[36:39], v[12:15], v[234:237], v[36:39]
	s_waitcnt vmcnt(8)
	v_mfma_f32_16x16x32_bf16 v[36:39], v[8:11], v[238:241], v[36:39]
	v_add_u32_e32 v31, 3072, v87
	s_waitcnt lgkmcnt(2)
	v_fmamk_f32 v32, v32, 0x3db504f3, v40
	v_fmac_f32_e32 v41, 0x3db504f3, v33
	v_fmamk_f32 v34, v34, 0x3db504f3, v42
	v_fmac_f32_e32 v43, 0x3db504f3, v35
	v_mov_b32_e32 v33, v41
	v_mov_b32_e32 v35, v43
	s_mov_b64 exec, s[6:7]
	ds_write_b128 v31, v[32:35]
	s_mov_b64 exec, -1
	v_subrev_u32_e32 v30, s80, v22
	v_max_i32_e32 v30, 0xffffff80, v30
	v_lshl_add_u32 v30, v30, 2, s72
	ds_read2st64_b32 v[40:41], v30 offset0:2 offset1:5
	ds_read2st64_b32 v[42:43], v30 offset0:8 offset1:11
	s_waitcnt vmcnt(7)
	v_mfma_f32_16x16x32_bf16 v[32:35], v[4:7], v[70:73], 0
	s_waitcnt vmcnt(6)
	v_mfma_f32_16x16x32_bf16 v[32:35], v[0:3], v[74:77], v[32:35]
	s_waitcnt vmcnt(5)
	v_mfma_f32_16x16x32_bf16 v[32:35], v[12:15], v[78:81], v[32:35]
	s_waitcnt vmcnt(4)
	v_mfma_f32_16x16x32_bf16 v[32:35], v[8:11], v[82:85], v[32:35]
	v_add_u32_e32 v31, 3328, v87
	s_waitcnt lgkmcnt(3)
	v_fmamk_f32 v36, v36, 0x3db504f3, v44
	v_fmac_f32_e32 v45, 0x3db504f3, v37
	v_fmamk_f32 v38, v38, 0x3db504f3, v46
	v_fmac_f32_e32 v47, 0x3db504f3, v39
	v_mov_b32_e32 v37, v45
	v_mov_b32_e32 v39, v47
	s_mov_b64 exec, s[6:7]
	ds_write_b128 v31, v[36:39]
	s_mov_b64 exec, -1
	v_subrev_u32_e32 v30, s80, v23
	v_max_i32_e32 v30, 0xffffff80, v30
	v_lshl_add_u32 v30, v30, 2, s72
	ds_read2st64_b32 v[44:45], v30 offset0:2 offset1:5
	ds_read2st64_b32 v[46:47], v30 offset0:8 offset1:11
	s_waitcnt vmcnt(3)
	v_mfma_f32_16x16x32_bf16 v[36:39], v[4:7], v[196:199], 0
	s_waitcnt vmcnt(2)
	v_mfma_f32_16x16x32_bf16 v[36:39], v[0:3], v[200:203], v[36:39]
	s_waitcnt vmcnt(1)
	v_mfma_f32_16x16x32_bf16 v[36:39], v[12:15], v[244:247], v[36:39]
	s_waitcnt vmcnt(0)
	v_mfma_f32_16x16x32_bf16 v[36:39], v[8:11], v[248:251], v[36:39]
	v_add_u32_e32 v31, 3584, v87
	s_waitcnt lgkmcnt(3)
	v_fmamk_f32 v32, v32, 0x3db504f3, v40
	v_fmac_f32_e32 v41, 0x3db504f3, v33
	v_fmamk_f32 v34, v34, 0x3db504f3, v42
	v_fmac_f32_e32 v43, 0x3db504f3, v35
	v_mov_b32_e32 v33, v41
	v_mov_b32_e32 v35, v43
	s_mov_b64 exec, s[6:7]
	ds_write_b128 v31, v[32:35]
	s_mov_b64 exec, -1
	s_nop 7
	s_nop 1
	v_add_u32_e32 v31, 3840, v87
	s_waitcnt lgkmcnt(0)
	v_fmamk_f32 v36, v36, 0x3db504f3, v44
	v_fmac_f32_e32 v45, 0x3db504f3, v37
	v_fmamk_f32 v38, v38, 0x3db504f3, v46
	v_fmac_f32_e32 v47, 0x3db504f3, v39
	v_mov_b32_e32 v37, v45
	v_mov_b32_e32 v39, v47
	s_mov_b64 exec, s[6:7]
	ds_write_b128 v31, v[36:39]
	s_mov_b64 exec, -1
	s_branch .LBB0_1532
